# thin split-K tiles of the out-proj and FFN-down GEMMs: two register sets, loads of the next two K groups in flight
# baseline (speedup 1.0000x reference)
.Lth4_pro2:
	s_cmp_gt_i32 s9, 7
	s_cbranch_scc1 .Lth4_A
	v_lshl_add_u64 v[96:97], v[60:61], 0, v[62:63]
	v_add_co_u32_e32 v88, vcc, 0x3c00000, v96
	v_lshl_add_u64 v[136:137], v[60:61], 0, v[58:59]
	s_nop 0
	v_addc_co_u32_e32 v89, vcc, 0, v97, vcc
	v_add_co_u32_e32 v92, vcc, 0x3c04000, v96
	s_nop 1
	v_addc_co_u32_e32 v93, vcc, 0, v97, vcc
	v_add_co_u32_e32 v98, vcc, 0x3c08000, v96
	global_load_dwordx4 v[88:91], v[88:89], off offset:2048
	s_nop 0
	global_load_dwordx4 v[92:95], v[92:93], off offset:2048
	v_addc_co_u32_e32 v99, vcc, 0, v97, vcc
	v_add_co_u32_e32 v100, vcc, 0x3c0c000, v96
	s_nop 1
	v_addc_co_u32_e32 v101, vcc, 0, v97, vcc
	v_add_co_u32_e32 v108, vcc, 0x21400000, v136
	global_load_dwordx4 v[96:99], v[98:99], off offset:2048
	s_nop 0
	global_load_dwordx4 v[100:103], v[100:101], off offset:2048
	v_addc_co_u32_e32 v109, vcc, 0, v137, vcc
	v_add_co_u32_e32 v112, vcc, 0x21404000, v136
	s_nop 1
	v_addc_co_u32_e32 v113, vcc, 0, v137, vcc
	v_add_co_u32_e32 v120, vcc, 0x21408000, v136
	global_load_dwordx4 v[108:111], v[108:109], off offset:2048
	s_nop 0
	global_load_dwordx4 v[112:115], v[112:113], off offset:2048
	v_addc_co_u32_e32 v121, vcc, 0, v137, vcc
	v_add_co_u32_e32 v124, vcc, 0x2140c000, v136
	s_nop 1
	v_addc_co_u32_e32 v125, vcc, 0, v137, vcc
	v_add_co_u32_e32 v128, vcc, 0x21410000, v136
	global_load_dwordx4 v[120:123], v[120:121], off offset:2048
	s_nop 0
	global_load_dwordx4 v[124:127], v[124:125], off offset:2048
	v_addc_co_u32_e32 v129, vcc, 0, v137, vcc
	v_add_co_u32_e32 v132, vcc, 0x21414000, v136
	s_nop 1
	v_addc_co_u32_e32 v133, vcc, 0, v137, vcc
	v_add_co_u32_e32 v138, vcc, 0x21418000, v136
	global_load_dwordx4 v[128:131], v[128:129], off offset:2048
	s_nop 0
	global_load_dwordx4 v[132:135], v[132:133], off offset:2048
	v_addc_co_u32_e32 v139, vcc, 0, v137, vcc
	v_add_co_u32_e32 v140, vcc, 0x2141c000, v136
	s_nop 1
	v_addc_co_u32_e32 v141, vcc, 0, v137, vcc
	global_load_dwordx4 v[136:139], v[138:139], off offset:2048
	s_nop 0
	global_load_dwordx4 v[140:143], v[140:141], off offset:2048
.Lth4_A:
	s_cmp_gt_i32 s9, 7
	s_cbranch_scc1 .Lth4_A_w0
	s_waitcnt vmcnt(12)
	s_branch .Lth4_A_go

.Lth4_A_go:
	ds_write_b128 v66, v[2:5]
	ds_write_b128 v66, v[6:9] offset:1088
	ds_write_b128 v66, v[10:13] offset:2176
	ds_write_b128 v66, v[14:17] offset:3264
	ds_write_b128 v66, v[22:25] offset:4352
	ds_write_b128 v66, v[26:29] offset:5440
	ds_write_b128 v66, v[34:37] offset:6528
	ds_write_b128 v66, v[38:41] offset:7616
	ds_write_b128 v66, v[42:45] offset:8704
	ds_write_b128 v66, v[46:49] offset:9792
	ds_write_b128 v66, v[50:53] offset:10880
	ds_write_b128 v66, v[54:57] offset:11968
	s_cmp_gt_i32 s9, -1
	s_cbranch_scc1 .Lth4_A_c
	v_lshl_add_u64 v[10:11], v[60:61], 0, v[62:63]
	v_add_co_u32_e32 v2, vcc, 0x3c00800, v10
	v_lshl_add_u64 v[50:51], v[60:61], 0, v[58:59]
	s_nop 0
	v_addc_co_u32_e32 v3, vcc, 0, v11, vcc
	v_add_co_u32_e32 v6, vcc, 0x3c04800, v10
	s_nop 1
	v_addc_co_u32_e32 v7, vcc, 0, v11, vcc
	v_add_co_u32_e32 v12, vcc, 0x3c08800, v10
	global_load_dwordx4 v[2:5], v[2:3], off offset:2048
	s_nop 0
	global_load_dwordx4 v[6:9], v[6:7], off offset:2048
	v_addc_co_u32_e32 v13, vcc, 0, v11, vcc
	v_add_co_u32_e32 v14, vcc, 0x3c0c800, v10
	s_nop 1
	v_addc_co_u32_e32 v15, vcc, 0, v11, vcc
	v_add_co_u32_e32 v22, vcc, 0x21400800, v50
	global_load_dwordx4 v[10:13], v[12:13], off offset:2048
	s_nop 0
	global_load_dwordx4 v[14:17], v[14:15], off offset:2048
	v_addc_co_u32_e32 v23, vcc, 0, v51, vcc
	v_add_co_u32_e32 v26, vcc, 0x21404800, v50
	s_nop 1
	v_addc_co_u32_e32 v27, vcc, 0, v51, vcc
	v_add_co_u32_e32 v34, vcc, 0x21408800, v50
	global_load_dwordx4 v[22:25], v[22:23], off offset:2048
	s_nop 0
	global_load_dwordx4 v[26:29], v[26:27], off offset:2048
	v_addc_co_u32_e32 v35, vcc, 0, v51, vcc
	v_add_co_u32_e32 v38, vcc, 0x2140c800, v50
	s_nop 1
	v_addc_co_u32_e32 v39, vcc, 0, v51, vcc
	v_add_co_u32_e32 v42, vcc, 0x21410800, v50
	global_load_dwordx4 v[34:37], v[34:35], off offset:2048
	s_nop 0
	global_load_dwordx4 v[38:41], v[38:39], off offset:2048
	v_addc_co_u32_e32 v43, vcc, 0, v51, vcc
	v_add_co_u32_e32 v46, vcc, 0x21414800, v50
	s_nop 1
	v_addc_co_u32_e32 v47, vcc, 0, v51, vcc
	v_add_co_u32_e32 v52, vcc, 0x21418800, v50
	global_load_dwordx4 v[42:45], v[42:43], off offset:2048
	s_nop 0
	global_load_dwordx4 v[46:49], v[46:47], off offset:2048
	v_addc_co_u32_e32 v53, vcc, 0, v51, vcc
	v_add_co_u32_e32 v54, vcc, 0x2141c800, v50
	s_nop 1
	v_addc_co_u32_e32 v55, vcc, 0, v51, vcc
	global_load_dwordx4 v[50:53], v[52:53], off offset:2048
	s_nop 0
	global_load_dwordx4 v[54:57], v[54:55], off offset:2048
.Lth4_A_c:
	s_waitcnt lgkmcnt(0)
	ds_read_b128 v[68:71], v67
	ds_read_b128 v[72:75], v67 offset:4352
	ds_read_b128 v[76:79], v67 offset:64
	ds_read_b128 v[80:83], v67 offset:4416
	s_add_i32 s9, s9, 8
	v_lshl_add_u64 v[60:61], v[60:61], 0, s[6:7]
	s_waitcnt lgkmcnt(2)
	v_mfma_f32_16x16x32_bf16 v[18:21], v[68:71], v[72:75], v[18:21]
	ds_read_b128 v[72:75], v67 offset:8704
	ds_read_b128 v[84:87], v67 offset:8768
	s_waitcnt lgkmcnt(1)
	v_mfma_f32_16x16x32_bf16 v[30:33], v[68:71], v[72:75], v[30:33]
	ds_read_b128 v[68:71], v67 offset:128
	v_mfma_f32_16x16x32_bf16 v[18:21], v[76:79], v[80:83], v[18:21]
	s_waitcnt lgkmcnt(1)
	v_mfma_f32_16x16x32_bf16 v[30:33], v[76:79], v[84:87], v[30:33]
	ds_read_b128 v[72:75], v67 offset:4480
	ds_read_b128 v[76:79], v67 offset:192
	ds_read_b128 v[80:83], v67 offset:4544
	s_waitcnt lgkmcnt(2)
	v_mfma_f32_16x16x32_bf16 v[18:21], v[68:71], v[72:75], v[18:21]
	ds_read_b128 v[72:75], v67 offset:8832
	ds_read_b128 v[84:87], v67 offset:8896
	s_waitcnt lgkmcnt(0)
	s_waitcnt lgkmcnt(1)
	v_mfma_f32_16x16x32_bf16 v[30:33], v[68:71], v[72:75], v[30:33]
	v_mfma_f32_16x16x32_bf16 v[18:21], v[76:79], v[80:83], v[18:21]
	s_waitcnt lgkmcnt(0)
	v_mfma_f32_16x16x32_bf16 v[30:33], v[76:79], v[84:87], v[30:33]
	s_cmp_gt_i32 s9, 15
	s_cbranch_scc1 .LBB0_995

.Lth4_B_go:
	ds_write_b128 v66, v[88:91]
	ds_write_b128 v66, v[92:95] offset:1088
	ds_write_b128 v66, v[96:99] offset:2176
	ds_write_b128 v66, v[100:103] offset:3264
	ds_write_b128 v66, v[108:111] offset:4352
	ds_write_b128 v66, v[112:115] offset:5440
	ds_write_b128 v66, v[120:123] offset:6528
	ds_write_b128 v66, v[124:127] offset:7616
	ds_write_b128 v66, v[128:131] offset:8704
	ds_write_b128 v66, v[132:135] offset:9792
	ds_write_b128 v66, v[136:139] offset:10880
	ds_write_b128 v66, v[140:143] offset:11968
	s_cmp_gt_i32 s9, -1
	s_cbranch_scc1 .Lth4_B_c
	v_lshl_add_u64 v[96:97], v[60:61], 0, v[62:63]
	v_add_co_u32_e32 v88, vcc, 0x3c00800, v96
	v_lshl_add_u64 v[136:137], v[60:61], 0, v[58:59]
	s_nop 0
	v_addc_co_u32_e32 v89, vcc, 0, v97, vcc
	v_add_co_u32_e32 v92, vcc, 0x3c04800, v96
	s_nop 1
	v_addc_co_u32_e32 v93, vcc, 0, v97, vcc
	v_add_co_u32_e32 v98, vcc, 0x3c08800, v96
	global_load_dwordx4 v[88:91], v[88:89], off offset:2048
	s_nop 0
	global_load_dwordx4 v[92:95], v[92:93], off offset:2048
	v_addc_co_u32_e32 v99, vcc, 0, v97, vcc
	v_add_co_u32_e32 v100, vcc, 0x3c0c800, v96
	s_nop 1
	v_addc_co_u32_e32 v101, vcc, 0, v97, vcc
	v_add_co_u32_e32 v108, vcc, 0x21400800, v136
	global_load_dwordx4 v[96:99], v[98:99], off offset:2048
	s_nop 0
	global_load_dwordx4 v[100:103], v[100:101], off offset:2048
	v_addc_co_u32_e32 v109, vcc, 0, v137, vcc
	v_add_co_u32_e32 v112, vcc, 0x21404800, v136
	s_nop 1
	v_addc_co_u32_e32 v113, vcc, 0, v137, vcc
	v_add_co_u32_e32 v120, vcc, 0x21408800, v136
	global_load_dwordx4 v[108:111], v[108:109], off offset:2048
	s_nop 0
	global_load_dwordx4 v[112:115], v[112:113], off offset:2048
	v_addc_co_u32_e32 v121, vcc, 0, v137, vcc
	v_add_co_u32_e32 v124, vcc, 0x2140c800, v136
	s_nop 1
	v_addc_co_u32_e32 v125, vcc, 0, v137, vcc
	v_add_co_u32_e32 v128, vcc, 0x21410800, v136
	global_load_dwordx4 v[120:123], v[120:121], off offset:2048
	s_nop 0
	global_load_dwordx4 v[124:127], v[124:125], off offset:2048
	v_addc_co_u32_e32 v129, vcc, 0, v137, vcc
	v_add_co_u32_e32 v132, vcc, 0x21414800, v136
	s_nop 1
	v_addc_co_u32_e32 v133, vcc, 0, v137, vcc
	v_add_co_u32_e32 v138, vcc, 0x21418800, v136
	global_load_dwordx4 v[128:131], v[128:129], off offset:2048
	s_nop 0
	global_load_dwordx4 v[132:135], v[132:133], off offset:2048
	v_addc_co_u32_e32 v139, vcc, 0, v137, vcc
	v_add_co_u32_e32 v140, vcc, 0x2141c800, v136
	s_nop 1
	v_addc_co_u32_e32 v141, vcc, 0, v137, vcc
	global_load_dwordx4 v[136:139], v[138:139], off offset:2048
	s_nop 0
	global_load_dwordx4 v[140:143], v[140:141], off offset:2048
.Lth4_B_c:
	s_waitcnt lgkmcnt(0)
	ds_read_b128 v[68:71], v67
	ds_read_b128 v[72:75], v67 offset:4352
	ds_read_b128 v[76:79], v67 offset:64
	ds_read_b128 v[80:83], v67 offset:4416
	s_add_i32 s9, s9, 8
	v_lshl_add_u64 v[60:61], v[60:61], 0, s[6:7]
	s_waitcnt lgkmcnt(2)
	v_mfma_f32_16x16x32_bf16 v[18:21], v[68:71], v[72:75], v[18:21]
	ds_read_b128 v[72:75], v67 offset:8704
	ds_read_b128 v[84:87], v67 offset:8768
	s_waitcnt lgkmcnt(1)
	v_mfma_f32_16x16x32_bf16 v[30:33], v[68:71], v[72:75], v[30:33]
	ds_read_b128 v[68:71], v67 offset:128
	v_mfma_f32_16x16x32_bf16 v[18:21], v[76:79], v[80:83], v[18:21]
	s_waitcnt lgkmcnt(1)
	v_mfma_f32_16x16x32_bf16 v[30:33], v[76:79], v[84:87], v[30:33]
	ds_read_b128 v[72:75], v67 offset:4480
	ds_read_b128 v[76:79], v67 offset:192
	ds_read_b128 v[80:83], v67 offset:4544
	s_waitcnt lgkmcnt(2)
	v_mfma_f32_16x16x32_bf16 v[18:21], v[68:71], v[72:75], v[18:21]
	ds_read_b128 v[72:75], v67 offset:8832
	ds_read_b128 v[84:87], v67 offset:8896
	s_waitcnt lgkmcnt(0)
	s_waitcnt lgkmcnt(1)
	v_mfma_f32_16x16x32_bf16 v[30:33], v[68:71], v[72:75], v[30:33]
	v_mfma_f32_16x16x32_bf16 v[18:21], v[76:79], v[80:83], v[18:21]
	s_waitcnt lgkmcnt(0)
	v_mfma_f32_16x16x32_bf16 v[30:33], v[76:79], v[84:87], v[30:33]
	s_cmp_gt_i32 s9, 15
	s_cbranch_scc1 .LBB0_995
	s_branch .Lth4_A

.Lth7_pro2:
	s_cmp_gt_i32 s7, 35
	s_cbranch_scc1 .Lth7_A
	v_lshl_add_u64 v[96:97], v[60:61], 0, v[62:63]
	v_add_co_u32_e32 v98, vcc, 0x7400000, v96
	v_lshl_add_u64 v[136:137], v[60:61], 0, v[58:59]
	s_nop 0
	v_addc_co_u32_e32 v99, vcc, 0, v97, vcc
	v_add_co_u32_e32 v100, vcc, 0x740b000, v96
	s_nop 1
	v_addc_co_u32_e32 v101, vcc, 0, v97, vcc
	global_load_dwordx4 v[88:91], v[98:99], off offset:2048
	global_load_dwordx4 v[92:95], v[100:101], off offset:2048
	v_add_co_u32_e32 v98, vcc, 0x7416000, v96
	s_nop 1
	v_addc_co_u32_e32 v99, vcc, 0, v97, vcc
	v_add_co_u32_e32 v100, vcc, 0x7421000, v96
	s_nop 1
	v_addc_co_u32_e32 v101, vcc, 0, v97, vcc
	v_add_co_u32_e32 v108, vcc, 0x31c00000, v136
	global_load_dwordx4 v[96:99], v[98:99], off offset:2048
	s_nop 0
	global_load_dwordx4 v[100:103], v[100:101], off offset:2048
	v_addc_co_u32_e32 v109, vcc, 0, v137, vcc
	v_add_co_u32_e32 v112, vcc, 0x31c0b000, v136
	s_nop 1
	v_addc_co_u32_e32 v113, vcc, 0, v137, vcc
	v_add_co_u32_e32 v120, vcc, 0x31c16000, v136
	global_load_dwordx4 v[108:111], v[108:109], off offset:2048
	s_nop 0
	global_load_dwordx4 v[112:115], v[112:113], off offset:2048
	v_addc_co_u32_e32 v121, vcc, 0, v137, vcc
	v_add_co_u32_e32 v124, vcc, 0x31c21000, v136
	s_nop 1
	v_addc_co_u32_e32 v125, vcc, 0, v137, vcc
	v_add_co_u32_e32 v128, vcc, 0x31c2c000, v136
	global_load_dwordx4 v[120:123], v[120:121], off offset:2048
	s_nop 0
	global_load_dwordx4 v[124:127], v[124:125], off offset:2048
	v_addc_co_u32_e32 v129, vcc, 0, v137, vcc
	v_add_co_u32_e32 v132, vcc, 0x31c37000, v136
	s_nop 1
	v_addc_co_u32_e32 v133, vcc, 0, v137, vcc
	v_add_co_u32_e32 v138, vcc, 0x31c42000, v136
	global_load_dwordx4 v[128:131], v[128:129], off offset:2048
	s_nop 0
	global_load_dwordx4 v[132:135], v[132:133], off offset:2048
	v_addc_co_u32_e32 v139, vcc, 0, v137, vcc
	v_add_co_u32_e32 v140, vcc, 0x31c4d000, v136
	s_nop 1
	v_addc_co_u32_e32 v141, vcc, 0, v137, vcc
	global_load_dwordx4 v[136:139], v[138:139], off offset:2048
	s_nop 0
	global_load_dwordx4 v[140:143], v[140:141], off offset:2048
.Lth7_A:
	s_cmp_gt_i32 s7, 35
	s_cbranch_scc1 .Lth7_A_w0
	s_waitcnt vmcnt(12)
	s_branch .Lth7_A_go

.Lth7_A_go:
	ds_write_b128 v66, v[2:5]
	ds_write_b128 v66, v[6:9] offset:1088
	ds_write_b128 v66, v[10:13] offset:2176
	ds_write_b128 v66, v[14:17] offset:3264
	ds_write_b128 v66, v[22:25] offset:4352
	ds_write_b128 v66, v[26:29] offset:5440
	ds_write_b128 v66, v[34:37] offset:6528
	ds_write_b128 v66, v[38:41] offset:7616
	ds_write_b128 v66, v[42:45] offset:8704
	ds_write_b128 v66, v[46:49] offset:9792
	ds_write_b128 v66, v[50:53] offset:10880
	ds_write_b128 v66, v[54:57] offset:11968
	s_cmp_gt_i32 s7, 27
	s_cbranch_scc1 .Lth7_A_c
	v_lshl_add_u64 v[10:11], v[60:61], 0, v[62:63]
	v_add_co_u32_e32 v12, vcc, 0x7400800, v10
	v_lshl_add_u64 v[50:51], v[60:61], 0, v[58:59]
	s_nop 0
	v_addc_co_u32_e32 v13, vcc, 0, v11, vcc
	v_add_co_u32_e32 v14, vcc, 0x740b800, v10
	s_nop 1
	v_addc_co_u32_e32 v15, vcc, 0, v11, vcc
	global_load_dwordx4 v[2:5], v[12:13], off offset:2048
	global_load_dwordx4 v[6:9], v[14:15], off offset:2048
	v_add_co_u32_e32 v12, vcc, 0x7416800, v10
	s_nop 1
	v_addc_co_u32_e32 v13, vcc, 0, v11, vcc
	v_add_co_u32_e32 v14, vcc, 0x7421800, v10
	s_nop 1
	v_addc_co_u32_e32 v15, vcc, 0, v11, vcc
	v_add_co_u32_e32 v22, vcc, 0x31c00800, v50
	global_load_dwordx4 v[10:13], v[12:13], off offset:2048
	s_nop 0
	global_load_dwordx4 v[14:17], v[14:15], off offset:2048
	v_addc_co_u32_e32 v23, vcc, 0, v51, vcc
	v_add_co_u32_e32 v26, vcc, 0x31c0b800, v50
	s_nop 1
	v_addc_co_u32_e32 v27, vcc, 0, v51, vcc
	v_add_co_u32_e32 v34, vcc, 0x31c16800, v50
	global_load_dwordx4 v[22:25], v[22:23], off offset:2048
	s_nop 0
	global_load_dwordx4 v[26:29], v[26:27], off offset:2048
	v_addc_co_u32_e32 v35, vcc, 0, v51, vcc
	v_add_co_u32_e32 v38, vcc, 0x31c21800, v50
	s_nop 1
	v_addc_co_u32_e32 v39, vcc, 0, v51, vcc
	v_add_co_u32_e32 v42, vcc, 0x31c2c800, v50
	global_load_dwordx4 v[34:37], v[34:35], off offset:2048
	s_nop 0
	global_load_dwordx4 v[38:41], v[38:39], off offset:2048
	v_addc_co_u32_e32 v43, vcc, 0, v51, vcc
	v_add_co_u32_e32 v46, vcc, 0x31c37800, v50
	s_nop 1
	v_addc_co_u32_e32 v47, vcc, 0, v51, vcc
	v_add_co_u32_e32 v52, vcc, 0x31c42800, v50
	global_load_dwordx4 v[42:45], v[42:43], off offset:2048
	s_nop 0
	global_load_dwordx4 v[46:49], v[46:47], off offset:2048
	v_addc_co_u32_e32 v53, vcc, 0, v51, vcc
	v_add_co_u32_e32 v54, vcc, 0x31c4d800, v50
	s_nop 1
	v_addc_co_u32_e32 v55, vcc, 0, v51, vcc
	global_load_dwordx4 v[50:53], v[52:53], off offset:2048
	s_nop 0
	global_load_dwordx4 v[54:57], v[54:55], off offset:2048
.Lth7_A_c:
	s_waitcnt lgkmcnt(0)
	ds_read_b128 v[68:71], v67
	ds_read_b128 v[72:75], v67 offset:4352
	ds_read_b128 v[76:79], v67 offset:64
	ds_read_b128 v[80:83], v67 offset:4416
	s_add_i32 s7, s7, 8
	v_lshl_add_u64 v[60:61], v[60:61], 0, s[2:3]
	s_waitcnt lgkmcnt(2)
	v_mfma_f32_16x16x32_bf16 v[18:21], v[68:71], v[72:75], v[18:21]
	ds_read_b128 v[72:75], v67 offset:8704
	ds_read_b128 v[84:87], v67 offset:8768
	s_waitcnt lgkmcnt(1)
	v_mfma_f32_16x16x32_bf16 v[30:33], v[68:71], v[72:75], v[30:33]
	ds_read_b128 v[68:71], v67 offset:128
	v_mfma_f32_16x16x32_bf16 v[18:21], v[76:79], v[80:83], v[18:21]
	s_waitcnt lgkmcnt(1)
	v_mfma_f32_16x16x32_bf16 v[30:33], v[76:79], v[84:87], v[30:33]
	ds_read_b128 v[72:75], v67 offset:4480
	ds_read_b128 v[76:79], v67 offset:192
	ds_read_b128 v[80:83], v67 offset:4544
	s_waitcnt lgkmcnt(2)
	v_mfma_f32_16x16x32_bf16 v[18:21], v[68:71], v[72:75], v[18:21]
	ds_read_b128 v[72:75], v67 offset:8832
	ds_read_b128 v[84:87], v67 offset:8896
	s_waitcnt lgkmcnt(0)
	s_waitcnt lgkmcnt(1)
	v_mfma_f32_16x16x32_bf16 v[30:33], v[68:71], v[72:75], v[30:33]
	v_mfma_f32_16x16x32_bf16 v[18:21], v[76:79], v[80:83], v[18:21]
	s_waitcnt lgkmcnt(0)
	v_mfma_f32_16x16x32_bf16 v[30:33], v[76:79], v[84:87], v[30:33]
	s_cmp_gt_i32 s7, 43
	s_cbranch_scc1 .LBB0_1229

.Lth7_B_go:
	ds_write_b128 v66, v[88:91]
	ds_write_b128 v66, v[92:95] offset:1088
	ds_write_b128 v66, v[96:99] offset:2176
	ds_write_b128 v66, v[100:103] offset:3264
	ds_write_b128 v66, v[108:111] offset:4352
	ds_write_b128 v66, v[112:115] offset:5440
	ds_write_b128 v66, v[120:123] offset:6528
	ds_write_b128 v66, v[124:127] offset:7616
	ds_write_b128 v66, v[128:131] offset:8704
	ds_write_b128 v66, v[132:135] offset:9792
	ds_write_b128 v66, v[136:139] offset:10880
	ds_write_b128 v66, v[140:143] offset:11968
	s_cmp_gt_i32 s7, 27
	s_cbranch_scc1 .Lth7_B_c
	v_lshl_add_u64 v[96:97], v[60:61], 0, v[62:63]
	v_add_co_u32_e32 v98, vcc, 0x7400800, v96
	v_lshl_add_u64 v[136:137], v[60:61], 0, v[58:59]
	s_nop 0
	v_addc_co_u32_e32 v99, vcc, 0, v97, vcc
	v_add_co_u32_e32 v100, vcc, 0x740b800, v96
	s_nop 1
	v_addc_co_u32_e32 v101, vcc, 0, v97, vcc
	global_load_dwordx4 v[88:91], v[98:99], off offset:2048
	global_load_dwordx4 v[92:95], v[100:101], off offset:2048
	v_add_co_u32_e32 v98, vcc, 0x7416800, v96
	s_nop 1
	v_addc_co_u32_e32 v99, vcc, 0, v97, vcc
	v_add_co_u32_e32 v100, vcc, 0x7421800, v96
	s_nop 1
	v_addc_co_u32_e32 v101, vcc, 0, v97, vcc
	v_add_co_u32_e32 v108, vcc, 0x31c00800, v136
	global_load_dwordx4 v[96:99], v[98:99], off offset:2048
	s_nop 0
	global_load_dwordx4 v[100:103], v[100:101], off offset:2048
	v_addc_co_u32_e32 v109, vcc, 0, v137, vcc
	v_add_co_u32_e32 v112, vcc, 0x31c0b800, v136
	s_nop 1
	v_addc_co_u32_e32 v113, vcc, 0, v137, vcc
	v_add_co_u32_e32 v120, vcc, 0x31c16800, v136
	global_load_dwordx4 v[108:111], v[108:109], off offset:2048
	s_nop 0
	global_load_dwordx4 v[112:115], v[112:113], off offset:2048
	v_addc_co_u32_e32 v121, vcc, 0, v137, vcc
	v_add_co_u32_e32 v124, vcc, 0x31c21800, v136
	s_nop 1
	v_addc_co_u32_e32 v125, vcc, 0, v137, vcc
	v_add_co_u32_e32 v128, vcc, 0x31c2c800, v136
	global_load_dwordx4 v[120:123], v[120:121], off offset:2048
	s_nop 0
	global_load_dwordx4 v[124:127], v[124:125], off offset:2048
	v_addc_co_u32_e32 v129, vcc, 0, v137, vcc
	v_add_co_u32_e32 v132, vcc, 0x31c37800, v136
	s_nop 1
	v_addc_co_u32_e32 v133, vcc, 0, v137, vcc
	v_add_co_u32_e32 v138, vcc, 0x31c42800, v136
	global_load_dwordx4 v[128:131], v[128:129], off offset:2048
	s_nop 0
	global_load_dwordx4 v[132:135], v[132:133], off offset:2048
	v_addc_co_u32_e32 v139, vcc, 0, v137, vcc
	v_add_co_u32_e32 v140, vcc, 0x31c4d800, v136
	s_nop 1
	v_addc_co_u32_e32 v141, vcc, 0, v137, vcc
	global_load_dwordx4 v[136:139], v[138:139], off offset:2048
	s_nop 0
	global_load_dwordx4 v[140:143], v[140:141], off offset:2048
.Lth7_B_c:
	s_waitcnt lgkmcnt(0)
	ds_read_b128 v[68:71], v67
	ds_read_b128 v[72:75], v67 offset:4352
	ds_read_b128 v[76:79], v67 offset:64
	ds_read_b128 v[80:83], v67 offset:4416
	s_add_i32 s7, s7, 8
	v_lshl_add_u64 v[60:61], v[60:61], 0, s[2:3]
	s_waitcnt lgkmcnt(2)
	v_mfma_f32_16x16x32_bf16 v[18:21], v[68:71], v[72:75], v[18:21]
	ds_read_b128 v[72:75], v67 offset:8704
	ds_read_b128 v[84:87], v67 offset:8768
	s_waitcnt lgkmcnt(1)
	v_mfma_f32_16x16x32_bf16 v[30:33], v[68:71], v[72:75], v[30:33]
	ds_read_b128 v[68:71], v67 offset:128
	v_mfma_f32_16x16x32_bf16 v[18:21], v[76:79], v[80:83], v[18:21]
	s_waitcnt lgkmcnt(1)
	v_mfma_f32_16x16x32_bf16 v[30:33], v[76:79], v[84:87], v[30:33]
	ds_read_b128 v[72:75], v67 offset:4480
	ds_read_b128 v[76:79], v67 offset:192
	ds_read_b128 v[80:83], v67 offset:4544
	s_waitcnt lgkmcnt(2)
	v_mfma_f32_16x16x32_bf16 v[18:21], v[68:71], v[72:75], v[18:21]
	ds_read_b128 v[72:75], v67 offset:8832
	ds_read_b128 v[84:87], v67 offset:8896
	s_waitcnt lgkmcnt(0)
	s_waitcnt lgkmcnt(1)
	v_mfma_f32_16x16x32_bf16 v[30:33], v[68:71], v[72:75], v[30:33]
	v_mfma_f32_16x16x32_bf16 v[18:21], v[76:79], v[80:83], v[18:21]
	s_waitcnt lgkmcnt(0)
	v_mfma_f32_16x16x32_bf16 v[30:33], v[76:79], v[84:87], v[30:33]
	s_cmp_gt_i32 s7, 43
	s_cbranch_scc1 .LBB0_1229
	s_branch .Lth7_A
